# stacked: rope-epilogue pipelining and norm-phase modulation loads hoisted (counted vmcnt) on top of the bounded GQA reference
# speedup vs baseline: 1.0188x; 1.0039x over previous
; __device__ __forceinline__ unsigned pk2(float lo, float hi) { return f2bf(lo) | (f2bf(hi) << 16); }
; __device__ __forceinline__ void norm_mod_phase(const float* lat, long lat_bs, const float* cx, long ctx_bs, const float* modl, int shoff, int scoff, bf16* XN, int skip_ctx, int gw, int NGW, float* xcopy, const float* part, int nkc, const float* pgate) {
;     ...
; #pragma unroll
;         for (int j = 0; j < 4; ++j) ss += (v[j].x * v[j].x + v[j].y * v[j].y) + (v[j].z * v[j].z + v[j].w * v[j].w);
;         if (xcopy && s == 4) {
;             const int b_ = row / TPB, cr = b_ * CTXL + (row - b_ * TPB); const f32x4* gp = (const f32x4*)(pgate + 4 * NMOD6) + lane;
;             f32x4 sm[4];
; #pragma unroll
;             for (int j = 0; j < 4; ++j) sm[j] = (f32x4){0.f, 0.f, 0.f, 0.f};
;             for (int kc = 0; kc < nkc; ++kc) { const f32x4* pp = (const f32x4*)(part + ((size_t)kc * 1024 + cr) * DMODEL) + lane;
; #pragma unroll
;                 for (int j = 0; j < 4; ++j) sm[j] += pp[64 * j]; }
;             f32x4* xc = (f32x4*)(xcopy + (size_t)row * DMODEL) + lane; ss = 0.f;
; #pragma unroll
;             for (int j = 0; j < 4; ++j) { v[j] += gp[64 * j] * sm[j]; xc[64 * j] = v[j]; ss += (v[j].x * v[j].x + v[j].y * v[j].y) + (v[j].z * v[j].z + v[j].w * v[j].w); } }
;         const float rstd = 1.0f / sqrtf(wave_sum(ss) * (1.0f / DMODEL) + EPS);
;         const f32x4* sh = (const f32x4*)(modl + s * NMOD6 + shoff) + lane; const f32x4* sc = (const f32x4*)(modl + s * NMOD6 + scoff) + lane;
;         v2u* o8 = (v2u*)(XN + (size_t)row * DMODEL) + lane;
; #pragma unroll
;         for (int j = 0; j < 4; ++j) { const f32x4 a = sh[64 * j], m = sc[64 * j]; const f32x4 y = v[j] * rstd * (m + 1.0f) + a; v2u w; w.x = pk2(y.x, y.y); w.y = pk2(y.z, y.w); o8[64 * j] = w; }
.LBB0_114:
	v_pk_mul_f32 v[44:45], v[14:15], v[14:15]
	v_pk_mul_f32 v[46:47], v[12:13], v[12:13]
	s_mulk_i32 s4, 0x1800
	v_mov_b32_e32 v48, v46
	v_mov_b32_e32 v49, v45
	v_pk_mov_b32 v[44:45], v[46:47], v[44:45] op_sel:[1,0]
	s_ashr_i32 s5, s4, 31
	v_pk_add_f32 v[44:45], v[44:45], v[48:49]
	s_lshl_b64 s[4:5], s[4:5], 2
	v_pk_add_f32 v[52:53], v[44:45], v[44:45] op_sel_hi:[0,1]
	v_pk_mul_f32 v[44:45], v[10:11], v[10:11]
	v_pk_mul_f32 v[46:47], v[8:9], v[8:9]
	s_add_u32 s48, s68, s4
	v_mov_b32_e32 v48, v46
	v_mov_b32_e32 v49, v45
	v_pk_mov_b32 v[44:45], v[46:47], v[44:45] op_sel:[1,0]
	s_addc_u32 s49, s69, s5
	v_pk_add_f32 v[44:45], v[44:45], v[48:49]
	v_lshl_add_u64 v[60:61], s[48:49], 0, v[32:33]
	v_pk_add_f32 v[54:55], v[44:45], v[44:45] op_sel_hi:[0,1]
	v_mul_f32_e32 v44, v4, v4
	v_add_co_u32_e32 v48, vcc, s1, v60
	v_pk_fma_f32 v[56:57], v[4:5], v[4:5], v[44:45] op_sel_hi:[1,1,0]
	v_mul_f32_e32 v44, v6, v6
	v_addc_co_u32_e32 v49, vcc, 0, v61, vcc
	v_pk_fma_f32 v[58:59], v[6:7], v[6:7], v[44:45] op_sel_hi:[1,1,0]
	global_load_dwordx4 v[44:47], v32, s[48:49]
	s_nop 0
	global_load_dwordx4 v[48:51], v[48:49], off
	v_mul_f32_e32 v56, v0, v0
	v_mul_f32_e32 v58, v1, v1
	v_mul_f32_e32 v54, v2, v2
	v_mul_f32_e32 v52, v3, v3
	v_pk_add_f32 v[56:57], v[56:57], v[58:59]
	v_pk_add_f32 v[52:53], v[54:55], v[52:53]
	s_waitcnt vmcnt(0)
	v_pk_add_f32 v[48:49], v[48:49], 1.0 op_sel_hi:[1,0]
	v_pk_add_f32 v[52:53], v[56:57], v[52:53]
	v_pk_add_f32 v[50:51], v[50:51], 1.0 op_sel_hi:[1,0]
	v_add_f32_e32 v52, v52, v53
	ds_bpermute_b32 v53, v38, v52
	s_waitcnt lgkmcnt(0)
	v_add_f32_e32 v52, v52, v53
	ds_bpermute_b32 v53, v39, v52
	s_waitcnt lgkmcnt(0)
	v_add_f32_e32 v52, v52, v53
	ds_bpermute_b32 v53, v40, v52
	s_waitcnt lgkmcnt(0)
	v_add_f32_e32 v52, v52, v53
	ds_bpermute_b32 v53, v41, v52
	s_waitcnt lgkmcnt(0)
	v_add_f32_e32 v52, v52, v53
	ds_bpermute_b32 v53, v42, v52
	s_waitcnt lgkmcnt(0)
	v_add_f32_e32 v52, v52, v53
	ds_bpermute_b32 v53, v43, v52
	s_waitcnt lgkmcnt(0)
	v_add_f32_e32 v52, v52, v53
	v_fmamk_f32 v52, v52, 0x3a800000, v36
	v_mul_f32_e32 v53, 0x4f800000, v52
	v_cmp_gt_f32_e32 vcc, s0, v52
	s_nop 1
	v_cndmask_b32_e32 v52, v52, v53, vcc
	v_sqrt_f32_e32 v53, v52
	s_nop 0
	v_add_u32_e32 v54, -1, v53
	v_add_u32_e32 v55, 1, v53
	v_fma_f32 v56, -v54, v53, v52
	v_fma_f32 v57, -v55, v53, v52
	v_cmp_ge_f32_e64 s[4:5], 0, v56
	s_nop 1
	v_cndmask_b32_e64 v53, v53, v54, s[4:5]
	v_cmp_lt_f32_e64 s[4:5], 0, v57
	s_nop 1
	v_cndmask_b32_e64 v53, v53, v55, s[4:5]
	v_mul_f32_e32 v54, 0x37800000, v53
	v_cndmask_b32_e32 v53, v53, v54, vcc
	v_cmp_class_f32_e32 vcc, v52, v37
	s_nop 1
	v_cndmask_b32_e32 v54, v53, v52, vcc
	v_div_scale_f32 v55, s[4:5], v54, v54, 1.0
	v_rcp_f32_e32 v56, v55
	v_div_scale_f32 v57, vcc, 1.0, v54, 1.0
	v_lshl_add_u64 v[52:53], v[60:61], 0, s[10:11]
	v_fma_f32 v58, -v55, v56, 1.0
	v_fmac_f32_e32 v56, v58, v56
	v_mul_f32_e32 v58, v57, v56
	v_fma_f32 v59, -v55, v58, v57
	v_fmac_f32_e32 v58, v59, v56
	v_fma_f32 v55, -v55, v58, v57
	v_div_fmas_f32 v55, v55, v56, v58
	v_div_fixup_f32 v54, v55, v54, 1.0
	v_pk_mul_f32 v[12:13], v[12:13], v[54:55] op_sel_hi:[1,0]
	v_pk_mul_f32 v[14:15], v[14:15], v[54:55] op_sel_hi:[1,0]
	v_pk_fma_f32 v[12:13], v[48:49], v[12:13], v[44:45]
	v_pk_fma_f32 v[14:15], v[50:51], v[14:15], v[46:47]
	v_bfe_u32 v44, v12, 16, 1
	v_bfe_u32 v45, v13, 16, 1
	v_add3_u32 v12, v12, v44, s3
	v_lshrrev_b32_e32 v12, 16, v12
	v_add3_u32 v13, v13, v45, s3
	v_and_or_b32 v12, v13, s14, v12
	v_bfe_u32 v13, v14, 16, 1
	v_add3_u32 v13, v14, v13, s3
	v_bfe_u32 v14, v15, 16, 1
	v_lshrrev_b32_e32 v13, 16, v13
	v_add3_u32 v14, v15, v14, s3
	v_and_or_b32 v13, v14, s14, v13
	global_store_dwordx2 v[34:35], v[12:13], off
	global_load_dwordx4 v[12:15], v[52:53], off offset:1024
	s_nop 0
	global_load_dwordx4 v[44:47], v32, s[48:49] offset:1024
	global_load_dwordx4 v[100:103], v[52:53], off offset:2048
	global_load_dwordx4 v[104:107], v32, s[48:49] offset:2048
	global_load_dwordx4 v[108:111], v[52:53], off offset:3072
	global_load_dwordx4 v[112:115], v32, s[48:49] offset:3072
	v_pk_mul_f32 v[8:9], v[8:9], v[54:55] op_sel_hi:[1,0]
	v_pk_mul_f32 v[10:11], v[10:11], v[54:55] op_sel_hi:[1,0]
	v_pk_mul_f32 v[4:5], v[4:5], v[54:55] op_sel_hi:[1,0]
	v_pk_mul_f32 v[6:7], v[6:7], v[54:55] op_sel_hi:[1,0]
	s_andn2_b64 vcc, exec, s[46:47]
	s_mov_b32 s4, s44
	s_waitcnt vmcnt(5)
	v_pk_add_f32 v[14:15], v[14:15], 1.0 op_sel_hi:[1,0]
	v_pk_add_f32 v[12:13], v[12:13], 1.0 op_sel_hi:[1,0]
	s_waitcnt vmcnt(4)
	v_pk_fma_f32 v[10:11], v[14:15], v[10:11], v[46:47]
	v_pk_fma_f32 v[8:9], v[12:13], v[8:9], v[44:45]
	v_bfe_u32 v14, v10, 16, 1
	v_bfe_u32 v12, v8, 16, 1
	v_bfe_u32 v13, v9, 16, 1
	v_bfe_u32 v15, v11, 16, 1
	v_add3_u32 v8, v8, v12, s3
	v_add3_u32 v10, v10, v14, s3
	v_add3_u32 v9, v9, v13, s3
	v_add3_u32 v11, v11, v15, s3
	v_lshrrev_b32_e32 v8, 16, v8
	v_lshrrev_b32_e32 v10, 16, v10
	v_and_or_b32 v8, v9, s14, v8
	v_and_or_b32 v9, v11, s14, v10
	global_store_dwordx2 v[34:35], v[8:9], off offset:512
	s_nop 0
	s_waitcnt vmcnt(4)
	v_pk_add_f32 v[10:11], v[102:103], 1.0 op_sel_hi:[1,0]
	v_pk_add_f32 v[8:9], v[100:101], 1.0 op_sel_hi:[1,0]
	s_waitcnt vmcnt(3)
	v_pk_fma_f32 v[6:7], v[6:7], v[10:11], v[106:107]
	v_pk_fma_f32 v[4:5], v[4:5], v[8:9], v[104:105]
	v_bfe_u32 v10, v6, 16, 1
	v_bfe_u32 v8, v4, 16, 1
	v_bfe_u32 v9, v5, 16, 1
	v_bfe_u32 v11, v7, 16, 1
	v_add3_u32 v4, v4, v8, s3
	v_add3_u32 v6, v6, v10, s3
	v_add3_u32 v5, v5, v9, s3
	v_add3_u32 v7, v7, v11, s3
	v_lshrrev_b32_e32 v4, 16, v4
	v_lshrrev_b32_e32 v6, 16, v6
	v_and_or_b32 v4, v5, s14, v4
	v_and_or_b32 v5, v7, s14, v6
	global_store_dwordx2 v[34:35], v[4:5], off offset:1024
	v_pk_mul_f32 v[52:53], v[0:1], v[54:55] op_sel_hi:[1,0]
	v_pk_mul_f32 v[54:55], v[2:3], v[54:55] op_sel_hi:[1,0]
	v_mov_b64_e32 v[0:1], v[28:29]
	v_mov_b64_e32 v[4:5], v[24:25]
	v_mov_b64_e32 v[8:9], v[20:21]
	v_mov_b64_e32 v[12:13], v[16:17]
	v_mov_b64_e32 v[2:3], v[30:31]
	v_mov_b64_e32 v[6:7], v[26:27]
	v_mov_b64_e32 v[10:11], v[22:23]
	v_mov_b64_e32 v[14:15], v[18:19]
	s_waitcnt vmcnt(3)
	v_pk_add_f32 v[46:47], v[110:111], 1.0 op_sel_hi:[1,0]
	v_pk_add_f32 v[44:45], v[108:109], 1.0 op_sel_hi:[1,0]
	s_waitcnt vmcnt(2)
	v_pk_fma_f32 v[46:47], v[54:55], v[46:47], v[114:115]
	v_pk_fma_f32 v[44:45], v[52:53], v[44:45], v[112:113]
	v_bfe_u32 v50, v46, 16, 1
	v_bfe_u32 v48, v44, 16, 1
	v_bfe_u32 v49, v45, 16, 1
	v_bfe_u32 v51, v47, 16, 1
	v_add3_u32 v44, v44, v48, s3
	v_add3_u32 v46, v46, v50, s3
	v_add3_u32 v45, v45, v49, s3
	v_add3_u32 v47, v47, v51, s3
	v_lshrrev_b32_e32 v44, 16, v44
	v_lshrrev_b32_e32 v46, 16, v46
	v_and_or_b32 v44, v45, s14, v44
	v_and_or_b32 v45, v47, s14, v46
	global_store_dwordx2 v[34:35], v[44:45], off offset:1536
	v_lshl_add_u64 v[34:35], v[34:35], 0, s[12:13]
	s_cbranch_vccz .LBB0_120

; __device__ __forceinline__ unsigned pk2(float lo, float hi) { return f2bf(lo) | (f2bf(hi) << 16); }
; __device__ __forceinline__ void norm_mod_phase(const float* lat, long lat_bs, const float* cx, long ctx_bs, const float* modl, int shoff, int scoff, bf16* XN, int skip_ctx, int gw, int NGW, float* xcopy, const float* part, int nkc, const float* pgate) {
;     ...
; #pragma unroll
;         for (int j = 0; j < 4; ++j) ss += (v[j].x * v[j].x + v[j].y * v[j].y) + (v[j].z * v[j].z + v[j].w * v[j].w);
;         if (xcopy && s == 4) {
;             const int b_ = row / TPB, cr = b_ * CTXL + (row - b_ * TPB); const f32x4* gp = (const f32x4*)(pgate + 4 * NMOD6) + lane;
;             f32x4 sm[4];
; #pragma unroll
;             for (int j = 0; j < 4; ++j) sm[j] = (f32x4){0.f, 0.f, 0.f, 0.f};
;             for (int kc = 0; kc < nkc; ++kc) { const f32x4* pp = (const f32x4*)(part + ((size_t)kc * 1024 + cr) * DMODEL) + lane;
; #pragma unroll
;                 for (int j = 0; j < 4; ++j) sm[j] += pp[64 * j]; }
;             f32x4* xc = (f32x4*)(xcopy + (size_t)row * DMODEL) + lane; ss = 0.f;
; #pragma unroll
;             for (int j = 0; j < 4; ++j) { v[j] += gp[64 * j] * sm[j]; xc[64 * j] = v[j]; ss += (v[j].x * v[j].x + v[j].y * v[j].y) + (v[j].z * v[j].z + v[j].w * v[j].w); } }
;         const float rstd = 1.0f / sqrtf(wave_sum(ss) * (1.0f / DMODEL) + EPS);
;         const f32x4* sh = (const f32x4*)(modl + s * NMOD6 + shoff) + lane; const f32x4* sc = (const f32x4*)(modl + s * NMOD6 + scoff) + lane;
;         v2u* o8 = (v2u*)(XN + (size_t)row * DMODEL) + lane;
; #pragma unroll
;         for (int j = 0; j < 4; ++j) { const f32x4 a = sh[64 * j], m = sc[64 * j]; const f32x4 y = v[j] * rstd * (m + 1.0f) + a; v2u w; w.x = pk2(y.x, y.y); w.y = pk2(y.z, y.w); o8[64 * j] = w; }
.LBB0_721:
	s_add_u32 s54, s54, s42
	s_mulk_i32 s4, 0x1800
	s_addc_u32 s55, s55, s43
	s_ashr_i32 s5, s4, 31
	s_lshl_b64 s[4:5], s[4:5], 2
	s_add_u32 s4, s68, s4
	s_addc_u32 s5, s69, s5
	v_lshl_add_u64 v[60:61], s[4:5], 0, v[32:33]
	v_add_co_u32_e32 v56, vcc, s12, v60
	ds_bpermute_b32 v51, v44, v50
	s_nop 0
	v_addc_co_u32_e32 v57, vcc, 0, v61, vcc
	global_load_dwordx4 v[52:55], v[56:57], off
	s_nop 0
	global_load_dwordx4 v[56:59], v[56:57], off offset:-4096
	s_lshl_b64 s[4:5], s[60:61], 11
	s_waitcnt lgkmcnt(0)
	v_add_f32_e32 v50, v50, v51
	ds_bpermute_b32 v51, v45, v50
	v_lshl_add_u64 v[62:63], v[36:37], 0, s[4:5]
	v_lshl_add_u64 v[40:41], v[40:41], 0, s[56:57]
	s_cmp_lt_i32 s54, 0x8400
	s_waitcnt lgkmcnt(0)
	v_add_f32_e32 v50, v50, v51
	ds_bpermute_b32 v51, v46, v50
	s_waitcnt lgkmcnt(0)
	v_add_f32_e32 v50, v50, v51
	ds_bpermute_b32 v51, v47, v50
	s_waitcnt lgkmcnt(0)
	v_add_f32_e32 v50, v50, v51
	ds_bpermute_b32 v51, v48, v50
	s_waitcnt lgkmcnt(0)
	v_add_f32_e32 v50, v50, v51
	ds_bpermute_b32 v51, v49, v50
	s_waitcnt lgkmcnt(0)
	v_add_f32_e32 v50, v50, v51
	v_fmamk_f32 v50, v50, 0x3a800000, v42
	v_mul_f32_e32 v51, 0x4f800000, v50
	v_cmp_gt_f32_e32 vcc, s7, v50
	s_waitcnt vmcnt(1)
	v_pk_add_f32 v[52:53], v[52:53], 1.0 op_sel_hi:[1,0]
	v_cndmask_b32_e32 v50, v50, v51, vcc
	v_sqrt_f32_e32 v51, v50
	s_nop 0
	v_add_u32_e32 v64, -1, v51
	v_add_u32_e32 v65, 1, v51
	v_fma_f32 v66, -v64, v51, v50
	v_fma_f32 v67, -v65, v51, v50
	v_cmp_ge_f32_e64 s[4:5], 0, v66
	s_nop 1
	v_cndmask_b32_e64 v51, v51, v64, s[4:5]
	v_cmp_lt_f32_e64 s[4:5], 0, v67
	s_nop 1
	v_cndmask_b32_e64 v51, v51, v65, s[4:5]
	v_mul_f32_e32 v64, 0x37800000, v51
	v_cndmask_b32_e32 v51, v51, v64, vcc
	v_cmp_class_f32_e32 vcc, v50, v43
	v_lshl_add_u64 v[64:65], v[60:61], 0, s[52:53]
	s_nop 0
	v_cndmask_b32_e32 v50, v51, v50, vcc
	v_div_scale_f32 v51, s[4:5], v50, v50, 1.0
	v_rcp_f32_e32 v66, v51
	v_div_scale_f32 v67, vcc, 1.0, v50, 1.0
	s_mov_b32 s4, s58
	v_fma_f32 v68, -v51, v66, 1.0
	v_fmac_f32_e32 v66, v68, v66
	v_mul_f32_e32 v68, v67, v66
	v_fma_f32 v69, -v51, v68, v67
	v_fmac_f32_e32 v68, v69, v66
	v_fma_f32 v51, -v51, v68, v67
	v_div_fmas_f32 v51, v51, v66, v68
	v_div_fixup_f32 v66, v51, v50, 1.0
	v_pk_mul_f32 v[12:13], v[12:13], v[66:67] op_sel_hi:[1,0]
	v_pk_mul_f32 v[14:15], v[14:15], v[66:67] op_sel_hi:[1,0]
	v_pk_add_f32 v[50:51], v[54:55], 1.0 op_sel_hi:[1,0]
	s_waitcnt vmcnt(0)
	v_pk_fma_f32 v[12:13], v[52:53], v[12:13], v[56:57]
	v_pk_fma_f32 v[14:15], v[50:51], v[14:15], v[58:59]
	v_bfe_u32 v50, v12, 16, 1
	v_bfe_u32 v52, v14, 16, 1
	v_bfe_u32 v51, v13, 16, 1
	v_bfe_u32 v53, v15, 16, 1
	v_add3_u32 v12, v12, v50, s13
	v_add3_u32 v14, v14, v52, s13
	v_add3_u32 v13, v13, v51, s13
	v_add3_u32 v15, v15, v53, s13
	v_lshrrev_b32_e32 v12, 16, v12
	v_lshrrev_b32_e32 v14, 16, v14
	v_and_or_b32 v12, v13, s14, v12
	v_and_or_b32 v13, v15, s14, v14
	global_store_dwordx2 v[62:63], v[12:13], off
	global_load_dwordx4 v[12:15], v[64:65], off offset:1024
	v_lshl_add_u64 v[54:55], v[60:61], 0, s[36:37]
	global_load_dwordx4 v[50:53], v[54:55], off offset:1024
	global_load_dwordx4 v[100:103], v[64:65], off offset:2048
	global_load_dwordx4 v[104:107], v[54:55], off offset:2048
	global_load_dwordx4 v[108:111], v[64:65], off offset:3072
	global_load_dwordx4 v[112:115], v[54:55], off offset:3072
	v_pk_mul_f32 v[8:9], v[8:9], v[66:67] op_sel_hi:[1,0]
	v_pk_mul_f32 v[10:11], v[10:11], v[66:67] op_sel_hi:[1,0]
	v_pk_mul_f32 v[4:5], v[4:5], v[66:67] op_sel_hi:[1,0]
	v_pk_mul_f32 v[6:7], v[6:7], v[66:67] op_sel_hi:[1,0]
	v_pk_mul_f32 v[58:59], v[0:1], v[66:67] op_sel_hi:[1,0]
	v_pk_mul_f32 v[60:61], v[2:3], v[66:67] op_sel_hi:[1,0]
	v_mov_b64_e32 v[0:1], v[28:29]
	v_mov_b64_e32 v[2:3], v[30:31]
	s_waitcnt vmcnt(5)
	v_pk_add_f32 v[14:15], v[14:15], 1.0 op_sel_hi:[1,0]
	v_pk_add_f32 v[12:13], v[12:13], 1.0 op_sel_hi:[1,0]
	s_waitcnt vmcnt(4)
	v_pk_fma_f32 v[10:11], v[14:15], v[10:11], v[52:53]
	v_pk_fma_f32 v[8:9], v[12:13], v[8:9], v[50:51]
	v_bfe_u32 v14, v10, 16, 1
	v_bfe_u32 v12, v8, 16, 1
	v_bfe_u32 v13, v9, 16, 1
	v_bfe_u32 v15, v11, 16, 1
	v_add3_u32 v8, v8, v12, s13
	v_add3_u32 v10, v10, v14, s13
	v_add3_u32 v9, v9, v13, s13
	v_add3_u32 v11, v11, v15, s13
	v_lshrrev_b32_e32 v8, 16, v8
	v_lshrrev_b32_e32 v10, 16, v10
	v_and_or_b32 v8, v9, s14, v8
	v_and_or_b32 v9, v11, s14, v10
	global_store_dwordx2 v[62:63], v[8:9], off offset:512
	s_nop 0
	s_waitcnt vmcnt(4)
	v_pk_add_f32 v[10:11], v[102:103], 1.0 op_sel_hi:[1,0]
	v_pk_add_f32 v[8:9], v[100:101], 1.0 op_sel_hi:[1,0]
	s_waitcnt vmcnt(3)
	v_pk_fma_f32 v[6:7], v[6:7], v[10:11], v[106:107]
	v_pk_fma_f32 v[4:5], v[4:5], v[8:9], v[104:105]
	v_bfe_u32 v10, v6, 16, 1
	v_bfe_u32 v8, v4, 16, 1
	v_bfe_u32 v9, v5, 16, 1
	v_bfe_u32 v11, v7, 16, 1
	v_add3_u32 v4, v4, v8, s13
	v_add3_u32 v6, v6, v10, s13
	v_add3_u32 v5, v5, v9, s13
	v_add3_u32 v7, v7, v11, s13
	v_lshrrev_b32_e32 v4, 16, v4
	v_lshrrev_b32_e32 v6, 16, v6
	v_and_or_b32 v4, v5, s14, v4
	v_and_or_b32 v5, v7, s14, v6
	global_store_dwordx2 v[62:63], v[4:5], off offset:1024
	s_nop 0
	v_mov_b64_e32 v[4:5], v[24:25]
	v_mov_b64_e32 v[8:9], v[20:21]
	v_mov_b64_e32 v[12:13], v[16:17]
	v_mov_b64_e32 v[6:7], v[26:27]
	v_mov_b64_e32 v[10:11], v[22:23]
	v_mov_b64_e32 v[14:15], v[18:19]
	s_waitcnt vmcnt(3)
	v_pk_add_f32 v[52:53], v[110:111], 1.0 op_sel_hi:[1,0]
	v_pk_add_f32 v[50:51], v[108:109], 1.0 op_sel_hi:[1,0]
	s_waitcnt vmcnt(2)
	v_pk_fma_f32 v[52:53], v[60:61], v[52:53], v[114:115]
	v_pk_fma_f32 v[50:51], v[58:59], v[50:51], v[112:113]
	v_bfe_u32 v56, v52, 16, 1
	v_bfe_u32 v54, v50, 16, 1
	v_bfe_u32 v55, v51, 16, 1
	v_bfe_u32 v57, v53, 16, 1
	v_add3_u32 v50, v50, v54, s13
	v_add3_u32 v52, v52, v56, s13
	v_add3_u32 v51, v51, v55, s13
	v_add3_u32 v53, v53, v57, s13
	v_lshrrev_b32_e32 v50, 16, v50
	v_lshrrev_b32_e32 v52, 16, v52
	v_and_or_b32 v50, v51, s14, v50
	v_and_or_b32 v51, v53, s14, v52
	global_store_dwordx2 v[62:63], v[50:51], off offset:1536
	s_cbranch_scc0 .LBB0_732

; __device__ __forceinline__ unsigned pk2(float lo, float hi) { return f2bf(lo) | (f2bf(hi) << 16); }
; __device__ __forceinline__ void norm_mod_phase(const float* lat, long lat_bs, const float* cx, long ctx_bs, const float* modl, int shoff, int scoff, bf16* XN, int skip_ctx, int gw, int NGW, float* xcopy, const float* part, int nkc, const float* pgate) {
;     ...
; #pragma unroll
;         for (int j = 0; j < 4; ++j) ss += (v[j].x * v[j].x + v[j].y * v[j].y) + (v[j].z * v[j].z + v[j].w * v[j].w);
;         if (xcopy && s == 4) {
;             const int b_ = row / TPB, cr = b_ * CTXL + (row - b_ * TPB); const f32x4* gp = (const f32x4*)(pgate + 4 * NMOD6) + lane;
;             f32x4 sm[4];
; #pragma unroll
;             for (int j = 0; j < 4; ++j) sm[j] = (f32x4){0.f, 0.f, 0.f, 0.f};
;             for (int kc = 0; kc < nkc; ++kc) { const f32x4* pp = (const f32x4*)(part + ((size_t)kc * 1024 + cr) * DMODEL) + lane;
; #pragma unroll
;                 for (int j = 0; j < 4; ++j) sm[j] += pp[64 * j]; }
;             f32x4* xc = (f32x4*)(xcopy + (size_t)row * DMODEL) + lane; ss = 0.f;
; #pragma unroll
;             for (int j = 0; j < 4; ++j) { v[j] += gp[64 * j] * sm[j]; xc[64 * j] = v[j]; ss += (v[j].x * v[j].x + v[j].y * v[j].y) + (v[j].z * v[j].z + v[j].w * v[j].w); } }
;         const float rstd = 1.0f / sqrtf(wave_sum(ss) * (1.0f / DMODEL) + EPS);
;         const f32x4* sh = (const f32x4*)(modl + s * NMOD6 + shoff) + lane; const f32x4* sc = (const f32x4*)(modl + s * NMOD6 + scoff) + lane;
;         v2u* o8 = (v2u*)(XN + (size_t)row * DMODEL) + lane;
; #pragma unroll
;         for (int j = 0; j < 4; ++j) { const f32x4 a = sh[64 * j], m = sc[64 * j]; const f32x4 y = v[j] * rstd * (m + 1.0f) + a; v2u w; w.x = pk2(y.x, y.y); w.y = pk2(y.z, y.w); o8[64 * j] = w; }
.LBB0_960:
	s_add_u32 s36, s36, s42
	s_mul_i32 s40, s57, 0x1800
	s_addc_u32 s37, s37, s43
	s_ashr_i32 s41, s40, 31
	s_lshl_b64 s[40:41], s[40:41], 2
	s_add_u32 s40, s86, s40
	s_addc_u32 s41, s38, s41
	v_lshl_add_u64 v[38:39], s[40:41], 0, v[40:41]
	v_add_co_u32_e32 v34, vcc, s54, v38
	ds_bpermute_b32 v33, v52, v32
	s_nop 0
	v_addc_co_u32_e32 v35, vcc, 0, v39, vcc
	global_load_dwordx4 v[34:37], v[34:35], off
	s_nop 0
	global_load_dwordx4 v[60:63], v40, s[40:41]
	s_lshl_b64 s[6:7], s[6:7], 11
	s_waitcnt lgkmcnt(0)
	v_add_f32_e32 v32, v32, v33
	ds_bpermute_b32 v33, v53, v32
	v_lshl_add_u64 v[50:51], v[46:47], 0, s[6:7]
	v_lshl_add_u64 v[38:39], v[38:39], 0, s[10:11]
	v_lshl_add_u64 v[48:49], v[48:49], 0, s[8:9]
	s_cmp_lt_i32 s36, 0x8400
	s_waitcnt lgkmcnt(0)
	v_add_f32_e32 v32, v32, v33
	ds_bpermute_b32 v33, v54, v32
	s_mov_b32 s57, s39
	s_waitcnt lgkmcnt(0)
	v_add_f32_e32 v32, v32, v33
	ds_bpermute_b32 v33, v55, v32
	s_waitcnt lgkmcnt(0)
	v_add_f32_e32 v32, v32, v33
	ds_bpermute_b32 v33, v56, v32
	s_waitcnt lgkmcnt(0)
	v_add_f32_e32 v32, v32, v33
	ds_bpermute_b32 v33, v57, v32
	s_waitcnt lgkmcnt(0)
	v_add_f32_e32 v32, v32, v33
	v_fmamk_f32 v32, v32, 0x3a800000, v58
	v_mul_f32_e32 v33, 0x4f800000, v32
	v_cmp_gt_f32_e32 vcc, s53, v32
	s_waitcnt vmcnt(1)
	v_pk_add_f32 v[34:35], v[34:35], 1.0 op_sel_hi:[1,0]
	v_cndmask_b32_e32 v32, v32, v33, vcc
	v_sqrt_f32_e32 v33, v32
	s_nop 0
	v_add_u32_e32 v64, -1, v33
	v_add_u32_e32 v65, 1, v33
	v_fma_f32 v66, -v64, v33, v32
	v_fma_f32 v67, -v65, v33, v32
	v_cmp_ge_f32_e64 s[6:7], 0, v66
	s_nop 1
	v_cndmask_b32_e64 v33, v33, v64, s[6:7]
	v_cmp_lt_f32_e64 s[6:7], 0, v67
	s_nop 1
	v_cndmask_b32_e64 v33, v33, v65, s[6:7]
	v_mul_f32_e32 v64, 0x37800000, v33
	v_cndmask_b32_e32 v33, v33, v64, vcc
	v_cmp_class_f32_e32 vcc, v32, v59
	s_nop 1
	v_cndmask_b32_e32 v32, v33, v32, vcc
	v_div_scale_f32 v33, s[6:7], v32, v32, 1.0
	v_rcp_f32_e32 v64, v33
	v_div_scale_f32 v65, vcc, 1.0, v32, 1.0
	v_fma_f32 v66, -v33, v64, 1.0
	v_fmac_f32_e32 v64, v66, v64
	v_mul_f32_e32 v66, v65, v64
	v_fma_f32 v67, -v33, v66, v65
	v_fmac_f32_e32 v66, v67, v64
	v_fma_f32 v33, -v33, v66, v65
	v_div_fmas_f32 v33, v33, v64, v66
	v_div_fixup_f32 v64, v33, v32, 1.0
	v_pk_mul_f32 v[28:29], v[28:29], v[64:65] op_sel_hi:[1,0]
	v_pk_mul_f32 v[30:31], v[30:31], v[64:65] op_sel_hi:[1,0]
	v_pk_add_f32 v[32:33], v[36:37], 1.0 op_sel_hi:[1,0]
	s_waitcnt vmcnt(0)
	v_pk_fma_f32 v[28:29], v[34:35], v[28:29], v[60:61]
	v_pk_fma_f32 v[30:31], v[32:33], v[30:31], v[62:63]
	v_bfe_u32 v32, v28, 16, 1
	v_bfe_u32 v34, v30, 16, 1
	v_bfe_u32 v33, v29, 16, 1
	v_bfe_u32 v35, v31, 16, 1
	v_add3_u32 v28, v28, v32, s55
	v_add3_u32 v30, v30, v34, s55
	v_add3_u32 v29, v29, v33, s55
	v_add3_u32 v31, v31, v35, s55
	v_lshrrev_b32_e32 v28, 16, v28
	v_lshrrev_b32_e32 v30, 16, v30
	v_and_or_b32 v28, v29, s56, v28
	v_and_or_b32 v29, v31, s56, v30
	global_store_dwordx2 v[50:51], v[28:29], off
	global_load_dwordx4 v[28:31], v[38:39], off offset:1024
	s_nop 0
	global_load_dwordx4 v[32:35], v40, s[40:41] offset:1024
	global_load_dwordx4 v[100:103], v[38:39], off offset:2048
	global_load_dwordx4 v[104:107], v40, s[40:41] offset:2048
	global_load_dwordx4 v[108:111], v[38:39], off offset:3072
	global_load_dwordx4 v[112:115], v40, s[40:41] offset:3072
	v_pk_mul_f32 v[8:9], v[8:9], v[64:65] op_sel_hi:[1,0]
	v_pk_mul_f32 v[10:11], v[10:11], v[64:65] op_sel_hi:[1,0]
	v_pk_mul_f32 v[4:5], v[4:5], v[64:65] op_sel_hi:[1,0]
	v_pk_mul_f32 v[6:7], v[6:7], v[64:65] op_sel_hi:[1,0]
	v_pk_mul_f32 v[60:61], v[0:1], v[64:65] op_sel_hi:[1,0]
	v_pk_mul_f32 v[62:63], v[2:3], v[64:65] op_sel_hi:[1,0]
	v_mov_b64_e32 v[0:1], v[12:13]
	v_mov_b64_e32 v[2:3], v[14:15]
	s_waitcnt vmcnt(5)
	v_pk_add_f32 v[30:31], v[30:31], 1.0 op_sel_hi:[1,0]
	v_pk_add_f32 v[28:29], v[28:29], 1.0 op_sel_hi:[1,0]
	s_waitcnt vmcnt(4)
	v_pk_fma_f32 v[10:11], v[30:31], v[10:11], v[34:35]
	v_pk_fma_f32 v[8:9], v[28:29], v[8:9], v[32:33]
	v_bfe_u32 v30, v10, 16, 1
	v_bfe_u32 v28, v8, 16, 1
	v_bfe_u32 v29, v9, 16, 1
	v_bfe_u32 v31, v11, 16, 1
	v_add3_u32 v8, v8, v28, s55
	v_add3_u32 v10, v10, v30, s55
	v_add3_u32 v9, v9, v29, s55
	v_add3_u32 v11, v11, v31, s55
	v_lshrrev_b32_e32 v8, 16, v8
	v_lshrrev_b32_e32 v10, 16, v10
	v_and_or_b32 v8, v9, s56, v8
	v_and_or_b32 v9, v11, s56, v10
	global_store_dwordx2 v[50:51], v[8:9], off offset:512
	s_nop 0
	s_waitcnt vmcnt(4)
	v_pk_add_f32 v[10:11], v[102:103], 1.0 op_sel_hi:[1,0]
	v_pk_add_f32 v[8:9], v[100:101], 1.0 op_sel_hi:[1,0]
	s_waitcnt vmcnt(3)
	v_pk_fma_f32 v[6:7], v[6:7], v[10:11], v[106:107]
	v_pk_fma_f32 v[4:5], v[4:5], v[8:9], v[104:105]
	v_bfe_u32 v10, v6, 16, 1
	v_bfe_u32 v8, v4, 16, 1
	v_bfe_u32 v9, v5, 16, 1
	v_bfe_u32 v11, v7, 16, 1
	v_add3_u32 v4, v4, v8, s55
	v_add3_u32 v6, v6, v10, s55
	v_add3_u32 v5, v5, v9, s55
	v_add3_u32 v7, v7, v11, s55
	v_lshrrev_b32_e32 v4, 16, v4
	v_lshrrev_b32_e32 v6, 16, v6
	v_and_or_b32 v4, v5, s56, v4
	v_and_or_b32 v5, v7, s56, v6
	global_store_dwordx2 v[50:51], v[4:5], off offset:1024
	s_nop 0
	v_mov_b64_e32 v[4:5], v[16:17]
	v_mov_b64_e32 v[8:9], v[20:21]
	v_mov_b64_e32 v[30:31], v[26:27]
	v_mov_b64_e32 v[6:7], v[18:19]
	v_mov_b64_e32 v[10:11], v[22:23]
	v_mov_b64_e32 v[28:29], v[24:25]
	s_waitcnt vmcnt(3)
	v_pk_add_f32 v[34:35], v[110:111], 1.0 op_sel_hi:[1,0]
	v_pk_add_f32 v[32:33], v[108:109], 1.0 op_sel_hi:[1,0]
	s_waitcnt vmcnt(2)
	v_pk_fma_f32 v[34:35], v[62:63], v[34:35], v[114:115]
	v_pk_fma_f32 v[32:33], v[60:61], v[32:33], v[112:113]
	v_bfe_u32 v38, v34, 16, 1
	v_bfe_u32 v36, v32, 16, 1
	v_bfe_u32 v37, v33, 16, 1
	v_bfe_u32 v39, v35, 16, 1
	v_add3_u32 v32, v32, v36, s55
	v_add3_u32 v34, v34, v38, s55
	v_add3_u32 v33, v33, v37, s55
	v_add3_u32 v35, v35, v39, s55
	v_lshrrev_b32_e32 v32, 16, v32
	v_lshrrev_b32_e32 v34, 16, v34
	v_and_or_b32 v32, v33, s56, v32
	v_and_or_b32 v33, v35, s56, v34
	global_store_dwordx2 v[50:51], v[32:33], off offset:1536
	s_cbranch_scc0 .LBB0_967

; __device__ __forceinline__ unsigned pk2(float lo, float hi) { return f2bf(lo) | (f2bf(hi) << 16); }
; __device__ __forceinline__ void norm_mod_phase(const float* lat, long lat_bs, const float* cx, long ctx_bs, const float* modl, int shoff, int scoff, bf16* XN, int skip_ctx, int gw, int NGW, float* xcopy, const float* part, int nkc, const float* pgate) {
;     ...
;         if (skip_ctx && s == 4) continue;
; #pragma unroll
;         for (int j = 0; j < 4; ++j) ss += (v[j].x * v[j].x + v[j].y * v[j].y) + (v[j].z * v[j].z + v[j].w * v[j].w);
;         if (xcopy && s == 4) {
;             const int b_ = row / TPB, cr = b_ * CTXL + (row - b_ * TPB); const f32x4* gp = (const f32x4*)(pgate + 4 * NMOD6) + lane;
;             f32x4 sm[4];
; #pragma unroll
;             for (int j = 0; j < 4; ++j) sm[j] = (f32x4){0.f, 0.f, 0.f, 0.f};
;             for (int kc = 0; kc < nkc; ++kc) { const f32x4* pp = (const f32x4*)(part + ((size_t)kc * 1024 + cr) * DMODEL) + lane;
; #pragma unroll
;                 for (int j = 0; j < 4; ++j) sm[j] += pp[64 * j]; }
;             f32x4* xc = (f32x4*)(xcopy + (size_t)row * DMODEL) + lane; ss = 0.f;
; #pragma unroll
;             for (int j = 0; j < 4; ++j) { v[j] += gp[64 * j] * sm[j]; xc[64 * j] = v[j]; ss += (v[j].x * v[j].x + v[j].y * v[j].y) + (v[j].z * v[j].z + v[j].w * v[j].w); } }
;         const float rstd = 1.0f / sqrtf(wave_sum(ss) * (1.0f / DMODEL) + EPS);
;         const f32x4* sh = (const f32x4*)(modl + s * NMOD6 + shoff) + lane; const f32x4* sc = (const f32x4*)(modl + s * NMOD6 + scoff) + lane;
;         v2u* o8 = (v2u*)(XN + (size_t)row * DMODEL) + lane;
; #pragma unroll
;         for (int j = 0; j < 4; ++j) { const f32x4 a = sh[64 * j], m = sc[64 * j]; const f32x4 y = v[j] * rstd * (m + 1.0f) + a; v2u w; w.x = pk2(y.x, y.y); w.y = pk2(y.z, y.w); o8[64 * j] = w; }
.LBB0_1375:
	s_cmp_eq_u32 s6, 4
	s_cbranch_scc1 .LBB0_1372
	v_pk_mul_f32 v[38:39], v[30:31], v[30:31]
	v_pk_mul_f32 v[40:41], v[28:29], v[28:29]
	s_mulk_i32 s6, 0x1800
	v_mov_b32_e32 v42, v40
	v_mov_b32_e32 v43, v39
	v_pk_mov_b32 v[38:39], v[40:41], v[38:39] op_sel:[1,0]
	s_ashr_i32 s7, s6, 31
	v_pk_add_f32 v[38:39], v[38:39], v[42:43]
	s_lshl_b64 s[6:7], s[6:7], 2
	v_pk_add_f32 v[46:47], v[38:39], v[38:39] op_sel_hi:[0,1]
	v_pk_mul_f32 v[38:39], v[26:27], v[26:27]
	v_pk_mul_f32 v[40:41], v[24:25], v[24:25]
	s_add_u32 s6, s86, s6
	v_mov_b32_e32 v42, v40
	v_mov_b32_e32 v43, v39
	v_pk_mov_b32 v[38:39], v[40:41], v[38:39] op_sel:[1,0]
	s_addc_u32 s7, s38, s7
	v_pk_add_f32 v[38:39], v[38:39], v[42:43]
	v_lshl_add_u64 v[54:55], s[6:7], 0, v[32:33]
	v_pk_add_f32 v[48:49], v[38:39], v[38:39] op_sel_hi:[0,1]
	v_mul_f32_e32 v38, v4, v4
	v_add_co_u32_e32 v56, vcc, s3, v54
	v_pk_fma_f32 v[50:51], v[4:5], v[4:5], v[38:39] op_sel_hi:[1,1,0]
	v_mul_f32_e32 v38, v6, v6
	v_addc_co_u32_e32 v57, vcc, 0, v55, vcc
	v_pk_fma_f32 v[52:53], v[6:7], v[6:7], v[38:39] op_sel_hi:[1,1,0]
	global_load_dwordx4 v[38:41], v[56:57], off offset:-4096
	global_load_dwordx4 v[42:45], v[56:57], off
	v_mul_f32_e32 v50, v0, v0
	v_mul_f32_e32 v52, v1, v1
	v_mul_f32_e32 v48, v2, v2
	v_mul_f32_e32 v46, v3, v3
	v_pk_add_f32 v[50:51], v[50:51], v[52:53]
	v_pk_add_f32 v[46:47], v[48:49], v[46:47]
	s_waitcnt vmcnt(0)
	v_pk_add_f32 v[42:43], v[42:43], 1.0 op_sel_hi:[1,0]
	v_pk_add_f32 v[46:47], v[50:51], v[46:47]
	v_pk_add_f32 v[44:45], v[44:45], 1.0 op_sel_hi:[1,0]
	v_add_f32_e32 v46, v46, v47
	ds_bpermute_b32 v47, v223, v46
	s_waitcnt lgkmcnt(0)
	v_add_f32_e32 v46, v46, v47
	ds_bpermute_b32 v47, v230, v46
	s_waitcnt lgkmcnt(0)
	v_add_f32_e32 v46, v46, v47
	ds_bpermute_b32 v47, v231, v46
	s_waitcnt lgkmcnt(0)
	v_add_f32_e32 v46, v46, v47
	ds_bpermute_b32 v47, v232, v46
	s_waitcnt lgkmcnt(0)
	v_add_f32_e32 v46, v46, v47
	ds_bpermute_b32 v47, v233, v46
	s_waitcnt lgkmcnt(0)
	v_add_f32_e32 v46, v46, v47
	ds_bpermute_b32 v47, v234, v46
	s_waitcnt lgkmcnt(0)
	v_add_f32_e32 v46, v46, v47
	v_fmamk_f32 v46, v46, 0x3a800000, v36
	v_mul_f32_e32 v47, 0x4f800000, v46
	v_cmp_gt_f32_e32 vcc, s1, v46
	s_nop 1
	v_cndmask_b32_e32 v46, v46, v47, vcc
	v_sqrt_f32_e32 v47, v46
	s_nop 0
	v_add_u32_e32 v48, -1, v47
	v_add_u32_e32 v49, 1, v47
	v_fma_f32 v50, -v48, v47, v46
	v_fma_f32 v51, -v49, v47, v46
	v_cmp_ge_f32_e64 s[6:7], 0, v50
	s_nop 1
	v_cndmask_b32_e64 v47, v47, v48, s[6:7]
	v_cmp_lt_f32_e64 s[6:7], 0, v51
	s_nop 1
	v_cndmask_b32_e64 v47, v47, v49, s[6:7]
	v_mul_f32_e32 v48, 0x37800000, v47
	v_cndmask_b32_e32 v47, v47, v48, vcc
	v_cmp_class_f32_e32 vcc, v46, v37
	s_nop 1
	v_cndmask_b32_e32 v48, v47, v46, vcc
	v_div_scale_f32 v49, s[6:7], v48, v48, 1.0
	v_rcp_f32_e32 v50, v49
	v_div_scale_f32 v51, vcc, 1.0, v48, 1.0
	v_lshl_add_u64 v[46:47], v[54:55], 0, s[10:11]
	v_fma_f32 v52, -v49, v50, 1.0
	v_fmac_f32_e32 v50, v52, v50
	v_mul_f32_e32 v52, v51, v50
	v_fma_f32 v53, -v49, v52, v51
	v_fmac_f32_e32 v52, v53, v50
	v_fma_f32 v49, -v49, v52, v51
	v_div_fmas_f32 v49, v49, v50, v52
	v_div_fixup_f32 v48, v49, v48, 1.0
	v_pk_mul_f32 v[28:29], v[28:29], v[48:49] op_sel_hi:[1,0]
	v_pk_mul_f32 v[30:31], v[30:31], v[48:49] op_sel_hi:[1,0]
	v_pk_fma_f32 v[28:29], v[42:43], v[28:29], v[38:39]
	v_pk_fma_f32 v[30:31], v[44:45], v[30:31], v[40:41]
	v_bfe_u32 v38, v28, 16, 1
	v_bfe_u32 v39, v29, 16, 1
	v_add3_u32 v28, v28, v38, s4
	v_lshrrev_b32_e32 v28, 16, v28
	v_add3_u32 v29, v29, v39, s4
	v_and_or_b32 v28, v29, s5, v28
	v_bfe_u32 v29, v30, 16, 1
	v_add3_u32 v29, v30, v29, s4
	v_bfe_u32 v30, v31, 16, 1
	v_lshrrev_b32_e32 v29, 16, v29
	v_add3_u32 v30, v31, v30, s4
	v_and_or_b32 v29, v30, s5, v29
	global_store_dwordx2 v[34:35], v[28:29], off
	global_load_dwordx4 v[28:31], v[46:47], off offset:1024
	v_lshl_add_u64 v[42:43], v[54:55], 0, s[8:9]
	global_load_dwordx4 v[38:41], v[42:43], off offset:1024
	global_load_dwordx4 v[100:103], v[46:47], off offset:2048
	global_load_dwordx4 v[104:107], v[42:43], off offset:2048
	global_load_dwordx4 v[108:111], v[46:47], off offset:3072
	global_load_dwordx4 v[112:115], v[42:43], off offset:3072
	v_pk_mul_f32 v[24:25], v[24:25], v[48:49] op_sel_hi:[1,0]
	v_pk_mul_f32 v[26:27], v[26:27], v[48:49] op_sel_hi:[1,0]
	v_pk_mul_f32 v[4:5], v[4:5], v[48:49] op_sel_hi:[1,0]
	v_pk_mul_f32 v[6:7], v[6:7], v[48:49] op_sel_hi:[1,0]
	v_pk_mul_f32 v[0:1], v[0:1], v[48:49] op_sel_hi:[1,0]
	v_pk_mul_f32 v[2:3], v[2:3], v[48:49] op_sel_hi:[1,0]
	s_waitcnt vmcnt(5)
	v_pk_add_f32 v[30:31], v[30:31], 1.0 op_sel_hi:[1,0]
	v_pk_add_f32 v[28:29], v[28:29], 1.0 op_sel_hi:[1,0]
	s_waitcnt vmcnt(4)
	v_pk_fma_f32 v[26:27], v[30:31], v[26:27], v[40:41]
	v_pk_fma_f32 v[24:25], v[28:29], v[24:25], v[38:39]
	v_bfe_u32 v30, v26, 16, 1
	v_bfe_u32 v28, v24, 16, 1
	v_bfe_u32 v29, v25, 16, 1
	v_bfe_u32 v31, v27, 16, 1
	v_add3_u32 v24, v24, v28, s4
	v_add3_u32 v26, v26, v30, s4
	v_add3_u32 v25, v25, v29, s4
	v_add3_u32 v27, v27, v31, s4
	v_lshrrev_b32_e32 v24, 16, v24
	v_lshrrev_b32_e32 v26, 16, v26
	v_and_or_b32 v24, v25, s5, v24
	v_and_or_b32 v25, v27, s5, v26
	global_store_dwordx2 v[34:35], v[24:25], off offset:512
	s_nop 0
	s_waitcnt vmcnt(4)
	v_pk_add_f32 v[26:27], v[102:103], 1.0 op_sel_hi:[1,0]
	v_pk_add_f32 v[24:25], v[100:101], 1.0 op_sel_hi:[1,0]
	s_waitcnt vmcnt(3)
	v_pk_fma_f32 v[6:7], v[6:7], v[26:27], v[106:107]
	v_pk_fma_f32 v[4:5], v[4:5], v[24:25], v[104:105]
	v_bfe_u32 v26, v6, 16, 1
	v_bfe_u32 v24, v4, 16, 1
	v_bfe_u32 v25, v5, 16, 1
	v_bfe_u32 v27, v7, 16, 1
	v_add3_u32 v4, v4, v24, s4
	v_add3_u32 v6, v6, v26, s4
	v_add3_u32 v5, v5, v25, s4
	v_add3_u32 v7, v7, v27, s4
	v_lshrrev_b32_e32 v4, 16, v4
	v_lshrrev_b32_e32 v6, 16, v6
	v_and_or_b32 v4, v5, s5, v4
	v_and_or_b32 v5, v7, s5, v6
	global_store_dwordx2 v[34:35], v[4:5], off offset:1024
	s_nop 0
	s_waitcnt vmcnt(3)
	v_pk_add_f32 v[6:7], v[110:111], 1.0 op_sel_hi:[1,0]
	v_pk_add_f32 v[4:5], v[108:109], 1.0 op_sel_hi:[1,0]
	s_waitcnt vmcnt(2)
	v_pk_fma_f32 v[2:3], v[2:3], v[6:7], v[114:115]
	v_pk_fma_f32 v[0:1], v[0:1], v[4:5], v[112:113]
	v_bfe_u32 v6, v2, 16, 1
	v_bfe_u32 v4, v0, 16, 1
	v_bfe_u32 v5, v1, 16, 1
	v_bfe_u32 v7, v3, 16, 1
	v_add3_u32 v0, v0, v4, s4
	v_add3_u32 v2, v2, v6, s4
	v_add3_u32 v1, v1, v5, s4
	v_add3_u32 v3, v3, v7, s4
	v_lshrrev_b32_e32 v0, 16, v0
	v_lshrrev_b32_e32 v2, 16, v2
	v_and_or_b32 v0, v1, s5, v0
	v_and_or_b32 v1, v3, s5, v2
	global_store_dwordx2 v[34:35], v[0:1], off offset:1536
	s_branch .LBB0_1372

; __global__ void __launch_bounds__(NTHREADS, 2) fwd_megakernel(Args a) {
;     ...
;     for (int lr = gw; lr < NBATCH * SEQ; lr += NGW) {
;         f32x4 v[4]; float ss = 0.f;
; #pragma unroll
;         for (int j = 0; j < 4; ++j) v[j] = vn[j];
;         if (lr + NGW < NBATCH * SEQ) { const int ln = lr + NGW, b = ln / SEQ, pos = ln - b * SEQ; const f32x4* xr = (const f32x4*)(X + ((size_t)b * TPB + CTXL + pos) * DMODEL) + lane;
; #pragma unroll
;             for (int j = 0; j < 4; ++j) vn[j] = xr[64 * j]; }
; #pragma unroll
;         for (int j = 0; j < 4; ++j) ss += (v[j].x * v[j].x + v[j].y * v[j].y) + (v[j].z * v[j].z + v[j].w * v[j].w);
;         const float rstd = 1.0f / sqrtf(wave_sum(ss) * (1.0f / DMODEL) + EPS);
;         const f32x4* gp = (const f32x4*)a.fgain + lane; f32x4* op = (f32x4*)(a.out + (size_t)lr * DMODEL) + lane;
; #pragma unroll
;         for (int j = 0; j < 4; ++j) op[64 * j] = v[j] * rstd * gp[64 * j];
.LBB0_1583:
	v_pk_mul_f32 v[40:41], v[8:9], v[8:9]
	v_pk_mul_f32 v[42:43], v[10:11], v[10:11]
	v_pk_mul_f32 v[44:45], v[12:13], v[12:13]
	v_pk_mul_f32 v[46:47], v[14:15], v[14:15]
	v_mov_b32_e32 v48, v44
	v_mov_b32_e32 v49, v47
	v_pk_mov_b32 v[44:45], v[44:45], v[46:47] op_sel:[1,0]
	v_mov_b32_e32 v46, v40
	v_mov_b32_e32 v47, v43
	v_pk_mov_b32 v[40:41], v[40:41], v[42:43] op_sel:[1,0]
	v_pk_add_f32 v[44:45], v[44:45], v[48:49]
	v_pk_add_f32 v[40:41], v[40:41], v[46:47]
	v_mul_f32_e32 v46, v0, v0
	v_mul_f32_e32 v47, v1, v1
	v_pk_add_f32 v[42:43], v[44:45], v[44:45] op_sel:[0,1] op_sel_hi:[1,0]
	v_pk_add_f32 v[40:41], v[40:41], v[40:41] op_sel:[0,1] op_sel_hi:[1,0]
	v_mov_b32_e32 v43, v46
	v_mov_b32_e32 v41, v47
	v_pk_add_f32 v[44:45], v[42:43], v[40:41]
	v_mul_f32_e32 v40, v5, v5
	v_pk_fma_f32 v[46:47], v[4:5], v[4:5], v[40:41] op_sel_hi:[1,1,0]
	global_load_dwordx4 v[40:43], v[34:35], off
	v_mul_f32_e32 v48, v2, v2
	v_mov_b32_e32 v47, v48
	v_mul_f32_e32 v48, v7, v7
	v_mul_f32_e32 v50, v3, v3
	v_pk_fma_f32 v[48:49], v[6:7], v[6:7], v[48:49] op_sel_hi:[1,1,0]
	s_add_u32 s6, s6, s42
	v_mov_b32_e32 v49, v50
	v_pk_add_f32 v[46:47], v[46:47], v[48:49]
	s_addc_u32 s7, s7, s43
	v_pk_add_f32 v[44:45], v[44:45], v[46:47]
	s_nop 0
	v_add_f32_e32 v44, v44, v45
	ds_bpermute_b32 v45, v223, v44
	s_waitcnt lgkmcnt(0)
	v_add_f32_e32 v44, v44, v45
	ds_bpermute_b32 v45, v230, v44
	s_waitcnt lgkmcnt(0)
	v_add_f32_e32 v44, v44, v45
	ds_bpermute_b32 v45, v231, v44
	s_waitcnt lgkmcnt(0)
	v_add_f32_e32 v44, v44, v45
	ds_bpermute_b32 v45, v232, v44
	s_waitcnt lgkmcnt(0)
	v_add_f32_e32 v44, v44, v45
	ds_bpermute_b32 v45, v233, v44
	s_waitcnt lgkmcnt(0)
	v_add_f32_e32 v44, v44, v45
	ds_bpermute_b32 v45, v234, v44
	s_waitcnt lgkmcnt(0)
	v_add_f32_e32 v44, v44, v45
	v_fmamk_f32 v44, v44, 0x3a800000, v38
	v_mul_f32_e32 v45, 0x4f800000, v44
	v_cmp_gt_f32_e32 vcc, s8, v44
	s_nop 1
	v_cndmask_b32_e32 v44, v44, v45, vcc
	v_sqrt_f32_e32 v45, v44
	s_nop 0
	v_add_u32_e32 v46, -1, v45
	v_add_u32_e32 v47, 1, v45
	v_fma_f32 v48, -v46, v45, v44
	v_fma_f32 v49, -v47, v45, v44
	v_cmp_ge_f32_e64 s[0:1], 0, v48
	s_nop 1
	v_cndmask_b32_e64 v45, v45, v46, s[0:1]
	v_cmp_lt_f32_e64 s[0:1], 0, v49
	s_nop 1
	v_cndmask_b32_e64 v45, v45, v47, s[0:1]
	v_mul_f32_e32 v46, 0x37800000, v45
	v_cndmask_b32_e32 v45, v45, v46, vcc
	v_cmp_class_f32_e32 vcc, v44, v39
	s_nop 1
	v_cndmask_b32_e32 v44, v45, v44, vcc
	v_div_scale_f32 v45, s[0:1], v44, v44, 1.0
	v_rcp_f32_e32 v46, v45
	v_div_scale_f32 v47, vcc, 1.0, v44, 1.0
	v_fma_f32 v48, -v45, v46, 1.0
	v_fmac_f32_e32 v46, v48, v46
	v_mul_f32_e32 v48, v47, v46
	v_fma_f32 v49, -v45, v48, v47
	v_fmac_f32_e32 v48, v49, v46
	v_fma_f32 v45, -v45, v48, v47
	v_div_fmas_f32 v45, v45, v46, v48
	v_div_fixup_f32 v44, v45, v44, 1.0
	v_pk_mul_f32 v[12:13], v[44:45], v[12:13] op_sel_hi:[0,1]
	v_pk_mul_f32 v[14:15], v[44:45], v[14:15] op_sel_hi:[0,1]
	s_waitcnt vmcnt(0)
	v_pk_mul_f32 v[14:15], v[14:15], v[42:43]
	v_pk_mul_f32 v[12:13], v[12:13], v[40:41]
	global_store_dwordx4 v[36:37], v[12:15], off
	global_load_dwordx4 v[12:15], v[34:35], off offset:1024
	global_load_dwordx4 v[100:103], v[34:35], off offset:2048
	global_load_dwordx4 v[104:107], v[34:35], off offset:3072
	v_pk_mul_f32 v[10:11], v[44:45], v[10:11] op_sel_hi:[0,1]
	v_pk_mul_f32 v[8:9], v[44:45], v[8:9] op_sel_hi:[0,1]
	v_pk_mul_f32 v[6:7], v[44:45], v[6:7] op_sel_hi:[0,1]
	v_pk_mul_f32 v[4:5], v[44:45], v[4:5] op_sel_hi:[0,1]
	v_pk_mul_f32 v[46:47], v[44:45], v[2:3] op_sel_hi:[0,1]
	v_pk_mul_f32 v[44:45], v[44:45], v[0:1] op_sel_hi:[0,1]
	s_and_b64 vcc, exec, s[4:5]
	v_mov_b32_e32 v0, v28
	v_mov_b32_e32 v1, v29
	v_mov_b32_e32 v2, v30
	v_mov_b32_e32 v3, v31
	s_waitcnt vmcnt(2)
	v_pk_mul_f32 v[8:9], v[8:9], v[12:13]
	v_pk_mul_f32 v[10:11], v[10:11], v[14:15]
	global_store_dwordx4 v[36:37], v[8:11], off offset:1024
	v_mov_b32_e32 v12, v16
	v_mov_b32_e32 v13, v17
	v_mov_b32_e32 v14, v18
	v_mov_b32_e32 v15, v19
	s_waitcnt vmcnt(2)
	v_pk_mul_f32 v[4:5], v[4:5], v[100:101]
	v_pk_mul_f32 v[6:7], v[6:7], v[102:103]
	global_store_dwordx4 v[36:37], v[4:7], off offset:2048
	v_mov_b32_e32 v8, v20
	v_mov_b32_e32 v9, v21
	v_mov_b32_e32 v10, v22
	v_mov_b32_e32 v11, v23
	v_mov_b32_e32 v4, v24
	v_mov_b32_e32 v5, v25
	v_mov_b32_e32 v6, v26
	v_mov_b32_e32 v7, v27
	s_waitcnt vmcnt(2)
	v_pk_mul_f32 v[16:17], v[44:45], v[104:105]
	v_pk_mul_f32 v[18:19], v[46:47], v[106:107]
	global_store_dwordx4 v[36:37], v[16:19], off offset:3072
	v_lshl_add_u64 v[36:37], v[36:37], 0, s[2:3]
	s_cbranch_vccnz .LBB0_1586
